# P3 job order: sliding-window units after the DSA jobs (the phase now ends on the shorter jobs)
# baseline (speedup 1.0000x reference)
; DI int opaque_tid() { int t = threadIdx.x; asm volatile("" : "+v"(t)); return t; }
; DI void dsa_job(const Params& p, int b, int tq0, char* lds) {
;   const int tid = opaque_tid(), lane = tid & 63, w = tid >> 6;
;   float* biasC = (float*)(lds + 143360);
;   int* btab = (int*)(lds + 143360 + 1024);
;   char* wl = lds + w * 17920;
;   float* Pl = (float*)wl;
;   int* kid = (int*)(wl + 8192);
;   const int tq = tq0 + w;
;   const size_t tok = (size_t)b * PP + tq;
;   const u16* Hb = p.H + (size_t)b * PP * LDH;
;   int kk[4], ku[4];
;   {
;     u32x2 iv = *(const u32x2*)(p.IDX + tok * 256 + 4 * lane);
;     kk[0] = iv[0] & 0xffff; kk[1] = iv[0] >> 16; kk[2] = iv[1] & 0xffff; kk[3] = iv[1] >> 16;
; #pragma unroll
;     for (int j = 0; j < 4; ++j) ku[j] = (kk[j] == 0xFFFF) ? LEAD : kk[j];
;     u32x4 kv4 = {(unsigned)ku[0], (unsigned)ku[1], (unsigned)ku[2], (unsigned)ku[3]};
;     ((u32x4*)kid)[lane] = kv4;
;   }
;   u32x4 gvp[4];
; #pragma unroll
;   for (int hh = 0; hh < 4; ++hh) gvp[hh] = *(const u32x4*)(p.H + tok * LDH + HG_C + (((lane >> 3) & 1) * 4 + hh) * 64 + (lane & 7) * 8);
;   __builtin_amdgcn_wave_barrier();
;   const int ksub = lane >> 4, g = (lane >> 3) & 1, dc = lane & 7;
;   {
;     const int r = lane & 31, h = lane >> 5, pc = lane & 15;
;     char* kst = wl + 9216;
;     bf16x8 qb[8];
; #pragma unroll
;     for (int ks = 0; ks < 8; ++ks) {
;       u32x4 v = {0u, 0u, 0u, 0u};
;       if (r < 8 && (ks >> 2) == (r >> 2)) v = *(const u32x4*)(p.H + tok * LDH + HQ_C + r * 64 + (ks & 3) * 16 + 8 * h);
; __global__ void __launch_bounds__(NTHREADS) mega(Params p) {
;     ...
;       for (;;) {
;         const int j = next_job(p.ctr + l * 2 + 1 + 8 * rep, lds, pending, NJ, par);
;         if (j >= NJ) break;
;         if (j < ND) {
;           const int qu = 32 - (j >> 5), rem = j & 31, kind = rem >> 4, b = (rem >> 3) & 1, head = rem & 7;
;           if (kind == 0) attn_unit<64, 0>(p, l, b, head, qu, lds);
;           else attn_unit<96, 1>(p, l, b, head, qu, lds);
;         } else if (j < ND + NS) {
;           const int u = j - ND;
;           attn_unit<64, 2>(p, l, (u >> 3) & 1, u & 7, u >> 4, lds);
;         } else {
;           const int u = j - ND - NS;
;           dsa_job(p, u & 1, LEAD + 8 * (u >> 1), lds);
.LBB0_2320:
	s_cmpk_gt_i32 s19, 0x41f
	s_cbranch_scc0 .LBB0_2376
	s_add_i32 s100, s19, 0x210
	s_sub_i32 s101, s19, 0x804
	s_cmpk_lt_u32 s19, 0xc24
	s_cselect_b32 s19, s100, s101
	s_cmpk_gt_u32 s19, 0x62f
	s_cbranch_scc0 .LBB0_2359
	s_lshl_b32 s0, s19, 2
	s_and_b32 s0, s0, 0x7ffffff8
	v_mov_b32_e32 v163, v152
	s_addk_i32 s0, 0xe7b0
	s_bitcmp1_b32 s19, 0
	s_waitcnt vmcnt(0)
	v_ashrrev_i32_e32 v12, 6, v163
	v_add_u32_e32 v158, s0, v12
	s_cselect_b32 s60, 0x2100, 0
	v_ashrrev_i32_e32 v159, 31, v158
	v_lshl_add_u64 v[0:1], s[60:61], 0, v[158:159]
	v_and_b32_e32 v153, 63, v163
	v_lshlrev_b64 v[4:5], 9, v[0:1]
	v_readlane_b32 s12, v240, 13
	v_readlane_b32 s13, v240, 14
	s_nop 0
	s_nop 0
	v_lshl_add_u64 v[4:5], s[12:13], 0, v[4:5]
	v_lshlrev_b32_e32 v2, 3, v153
	v_lshl_add_u64 v[4:5], v[4:5], 0, v[2:3]
	v_readlane_b32 s8, v241, 24
	v_readlane_b32 s9, v241, 25
	global_load_dwordx2 v[10:11], v[4:5], off
	s_nop 0
	v_mov_b64_e32 v[4:5], s[8:9]
	v_lshlrev_b32_e32 v2, 3, v163
	v_mad_u64_u32 v[6:7], s[0:1], v0, s53, v[4:5]
	v_and_b32_e32 v2, 56, v2
	v_mad_i32_i24 v7, v1, s53, v7
	v_lshlrev_b32_e32 v2, 1, v2
	v_lshlrev_b32_e32 v8, 6, v163
	v_lshl_add_u64 v[4:5], v[6:7], 0, v[2:3]
	v_and_b32_e32 v8, 0x200, v8
	v_mov_b32_e32 v9, v3
	v_lshl_add_u64 v[4:5], v[4:5], 0, v[8:9]
	s_mov_b64 s[0:1], 0x1d00
	v_lshl_add_u64 v[8:9], v[4:5], 0, s[0:1]
	s_movk_i32 s0, 0x1000
	v_add_co_u32_e32 v4, vcc, s0, v4
	s_movk_i32 s0, 0x4600
	s_nop 0
	v_addc_co_u32_e32 v5, vcc, 0, v5, vcc
	global_load_dwordx4 v[44:47], v[8:9], off offset:128
	global_load_dwordx4 v[40:43], v[8:9], off offset:256
	global_load_dwordx4 v[48:51], v[4:5], off offset:3328
	global_load_dwordx4 v[36:39], v[8:9], off offset:384
	v_and_b32_e32 v9, 31, v163
	v_mov_b32_e32 v13, v3
	v_bfe_u32 v4, v163, 5, 1
	v_mul_lo_u32 v8, v12, s0
	v_lshlrev_b32_e32 v12, 7, v9
	v_mov_b32_e32 v5, v3
	v_lshlrev_b32_e32 v4, 4, v4
	v_lshl_add_u64 v[6:7], v[6:7], 0, v[12:13]
	v_lshl_add_u64 v[6:7], v[6:7], 0, v[4:5]
	s_mov_b64 s[0:1], 0x1300
	s_mov_b32 s2, 0xffff
	v_and_b32_e32 v14, 28, v163
	v_add_u32_e32 v159, 0, v8
	v_lshl_add_u64 v[6:7], v[6:7], 0, s[0:1]
	v_mov_b32_e32 v56, 0
	v_mov_b32_e32 v60, 0
	v_mov_b32_e32 v61, 0
	v_mov_b32_e32 v62, 0
	v_cmp_eq_u32_e32 vcc, 0, v14
	v_lshl_add_u32 v14, v153, 4, v159
	v_mov_b32_e32 v63, 0
	s_waitcnt vmcnt(4)
	v_and_b32_e32 v5, 0xffff, v10
	v_lshrrev_b32_e32 v10, 16, v10
	v_and_b32_e32 v12, 0xffff, v11
	v_lshrrev_b32_e32 v11, 16, v11
	v_cmp_eq_u32_e64 s[4:5], s2, v5
	v_cmp_eq_u32_e64 s[6:7], s2, v10
	v_cmp_eq_u32_e64 s[0:1], s2, v12
	v_cmp_eq_u32_e64 s[2:3], s2, v11
	v_cndmask_b32_e64 v52, v5, v202, s[4:5]
	v_cndmask_b32_e64 v53, v10, v202, s[6:7]
	v_cndmask_b32_e64 v54, v12, v202, s[0:1]
	v_cndmask_b32_e64 v55, v11, v202, s[2:3]
	ds_write_b128 v14, v[52:55] offset:8192
	s_and_saveexec_b64 s[8:9], vcc
	s_cbranch_execz .LBB0_2324
	global_load_dwordx4 v[60:63], v[6:7], off
